# tailfin: batched split-K slab loads; GEMM K-loop: LDS-DMA via scalar base + 32-bit lane offset (no per-load 64-bit VALU add)
# speedup vs baseline: 1.0114x; 1.0114x over previous
; #define GAS __attribute__((address_space(1)))
; #define GAS __attribute__((address_space(1)))
; DI float bflo(unsigned w) { return __uint_as_float(w << 16); }
; DI float bfhi(unsigned w) { return __uint_as_float(w & 0xffff0000u); }
; DI void phase_tailfin(bf16_t* HB, const float* T, int nsl, float* ss, LAS float* sl) {
;     ...
;         const size_t row = 65536 + r; GAS unsigned* hp = (GAS unsigned*)(HB + row * 1024) + tid; GAS const f32x2v* tp = (GAS const f32x2v*)(T + (size_t)r * 1024) + tid;
;         const unsigned h = *hp; float v0 = bflo(h), v1 = bfhi(h);
;         float t0 = 0.f, t1 = 0.f;
;         for (int s = 0; s < nsl; ++s) { const f32x2v t = tp[(size_t)s * (256 * 512)]; t0 += t[0]; t1 += t[1]; }
;         v0 += t0; v1 += t1;
.LBB0_165:
	s_add_i32 s24, s22, 0x10000
	s_ashr_i32 s25, s24, 31
	s_lshl_b64 s[26:27], s[24:25], 11
	s_add_u32 s26, s20, s26
	s_addc_u32 s27, s21, s27
	v_lshl_add_u64 v[4:5], v[0:1], 2, s[26:27]
	global_load_dword v11, v[4:5], off
	v_mov_b32_e32 v7, 0
	s_andn2_b64 vcc, exec, s[16:17]
	v_mov_b32_e32 v6, v7
	s_cbranch_vccnz .LBB0_168
	s_ashr_i32 s23, s22, 31
	s_lshl_b64 s[26:27], s[22:23], 12
	v_readlane_b32 s28, v254, 30
	v_readlane_b32 s29, v254, 31
	s_add_u32 s26, s28, s26
	s_addc_u32 s27, s29, s27
	v_mov_b32_e32 v6, 0
	v_lshl_add_u64 v[8:9], v[0:1], 3, s[26:27]
	s_mov_b32 s2, s12
	v_mov_b32_e32 v7, v6
	s_cmp_eq_u32 s2, 22
	s_cbranch_scc1 .Ltailfin_22
	s_cmp_eq_u32 s2, 8
	s_cbranch_scc1 .Ltailfin_8
	s_branch .LBB0_167
.Ltailfin_22:
	s_mov_b64 s[26:27], 0x100000
	global_load_dwordx2 v[16:17], v[8:9], off
	v_lshl_add_u64 v[8:9], v[8:9], 0, s[26:27]
	global_load_dwordx2 v[18:19], v[8:9], off
	v_lshl_add_u64 v[8:9], v[8:9], 0, s[26:27]
	global_load_dwordx2 v[20:21], v[8:9], off
	v_lshl_add_u64 v[8:9], v[8:9], 0, s[26:27]
	global_load_dwordx2 v[22:23], v[8:9], off
	v_lshl_add_u64 v[8:9], v[8:9], 0, s[26:27]
	global_load_dwordx2 v[24:25], v[8:9], off
	v_lshl_add_u64 v[8:9], v[8:9], 0, s[26:27]
	global_load_dwordx2 v[26:27], v[8:9], off
	v_lshl_add_u64 v[8:9], v[8:9], 0, s[26:27]
	global_load_dwordx2 v[28:29], v[8:9], off
	v_lshl_add_u64 v[8:9], v[8:9], 0, s[26:27]
	global_load_dwordx2 v[30:31], v[8:9], off
	v_lshl_add_u64 v[8:9], v[8:9], 0, s[26:27]
	global_load_dwordx2 v[32:33], v[8:9], off
	v_lshl_add_u64 v[8:9], v[8:9], 0, s[26:27]
	global_load_dwordx2 v[34:35], v[8:9], off
	v_lshl_add_u64 v[8:9], v[8:9], 0, s[26:27]
	global_load_dwordx2 v[36:37], v[8:9], off
	v_lshl_add_u64 v[8:9], v[8:9], 0, s[26:27]
	global_load_dwordx2 v[38:39], v[8:9], off
	v_lshl_add_u64 v[8:9], v[8:9], 0, s[26:27]
	global_load_dwordx2 v[40:41], v[8:9], off
	v_lshl_add_u64 v[8:9], v[8:9], 0, s[26:27]
	global_load_dwordx2 v[42:43], v[8:9], off
	v_lshl_add_u64 v[8:9], v[8:9], 0, s[26:27]
	global_load_dwordx2 v[44:45], v[8:9], off
	v_lshl_add_u64 v[8:9], v[8:9], 0, s[26:27]
	global_load_dwordx2 v[46:47], v[8:9], off
	v_lshl_add_u64 v[8:9], v[8:9], 0, s[26:27]
	global_load_dwordx2 v[48:49], v[8:9], off
	v_lshl_add_u64 v[8:9], v[8:9], 0, s[26:27]
	global_load_dwordx2 v[50:51], v[8:9], off
	v_lshl_add_u64 v[8:9], v[8:9], 0, s[26:27]
	global_load_dwordx2 v[52:53], v[8:9], off
	v_lshl_add_u64 v[8:9], v[8:9], 0, s[26:27]
	global_load_dwordx2 v[54:55], v[8:9], off
	v_lshl_add_u64 v[8:9], v[8:9], 0, s[26:27]
	global_load_dwordx2 v[56:57], v[8:9], off
	v_lshl_add_u64 v[8:9], v[8:9], 0, s[26:27]
	global_load_dwordx2 v[58:59], v[8:9], off
	s_waitcnt vmcnt(0)
	v_pk_add_f32 v[6:7], v[6:7], v[16:17]
	s_nop 0
	v_pk_add_f32 v[6:7], v[6:7], v[18:19]
	s_nop 0
	v_pk_add_f32 v[6:7], v[6:7], v[20:21]
	s_nop 0
	v_pk_add_f32 v[6:7], v[6:7], v[22:23]
	s_nop 0
	v_pk_add_f32 v[6:7], v[6:7], v[24:25]
	s_nop 0
	v_pk_add_f32 v[6:7], v[6:7], v[26:27]
	s_nop 0
	v_pk_add_f32 v[6:7], v[6:7], v[28:29]
	s_nop 0
	v_pk_add_f32 v[6:7], v[6:7], v[30:31]
	s_nop 0
	v_pk_add_f32 v[6:7], v[6:7], v[32:33]
	s_nop 0
	v_pk_add_f32 v[6:7], v[6:7], v[34:35]
	s_nop 0
	v_pk_add_f32 v[6:7], v[6:7], v[36:37]
	s_nop 0
	v_pk_add_f32 v[6:7], v[6:7], v[38:39]
	s_nop 0
	v_pk_add_f32 v[6:7], v[6:7], v[40:41]
	s_nop 0
	v_pk_add_f32 v[6:7], v[6:7], v[42:43]
	s_nop 0
	v_pk_add_f32 v[6:7], v[6:7], v[44:45]
	s_nop 0
	v_pk_add_f32 v[6:7], v[6:7], v[46:47]
	s_nop 0
	v_pk_add_f32 v[6:7], v[6:7], v[48:49]
	s_nop 0
	v_pk_add_f32 v[6:7], v[6:7], v[50:51]
	s_nop 0
	v_pk_add_f32 v[6:7], v[6:7], v[52:53]
	s_nop 0
	v_pk_add_f32 v[6:7], v[6:7], v[54:55]
	s_nop 0
	v_pk_add_f32 v[6:7], v[6:7], v[56:57]
	s_nop 0
	v_pk_add_f32 v[6:7], v[6:7], v[58:59]
	s_branch .LBB0_168
.Ltailfin_8:
	s_mov_b64 s[26:27], 0x100000
	global_load_dwordx2 v[16:17], v[8:9], off
	v_lshl_add_u64 v[8:9], v[8:9], 0, s[26:27]
	global_load_dwordx2 v[18:19], v[8:9], off
	v_lshl_add_u64 v[8:9], v[8:9], 0, s[26:27]
	global_load_dwordx2 v[20:21], v[8:9], off
	v_lshl_add_u64 v[8:9], v[8:9], 0, s[26:27]
	global_load_dwordx2 v[22:23], v[8:9], off
	v_lshl_add_u64 v[8:9], v[8:9], 0, s[26:27]
	global_load_dwordx2 v[24:25], v[8:9], off
	v_lshl_add_u64 v[8:9], v[8:9], 0, s[26:27]
	global_load_dwordx2 v[26:27], v[8:9], off
	v_lshl_add_u64 v[8:9], v[8:9], 0, s[26:27]
	global_load_dwordx2 v[28:29], v[8:9], off
	v_lshl_add_u64 v[8:9], v[8:9], 0, s[26:27]
	global_load_dwordx2 v[30:31], v[8:9], off
	s_waitcnt vmcnt(0)
	v_pk_add_f32 v[6:7], v[6:7], v[16:17]
	s_nop 0
	v_pk_add_f32 v[6:7], v[6:7], v[18:19]
	s_nop 0
	v_pk_add_f32 v[6:7], v[6:7], v[20:21]
	s_nop 0
	v_pk_add_f32 v[6:7], v[6:7], v[22:23]
	s_nop 0
	v_pk_add_f32 v[6:7], v[6:7], v[24:25]
	s_nop 0
	v_pk_add_f32 v[6:7], v[6:7], v[26:27]
	s_nop 0
	v_pk_add_f32 v[6:7], v[6:7], v[28:29]
	s_nop 0
	v_pk_add_f32 v[6:7], v[6:7], v[30:31]
	s_branch .LBB0_168

; #define PG8_STAGE(bufoff, gbase, voff) do { _Pragma("unroll") for (int _i = 0; _i < 2; ++_i) \
;         __builtin_amdgcn_global_load_lds((const unsigned*)((const char*)(gbase) + (voff)[_i]), (PG8_LAS unsigned*)(lds + (bufoff) + ldsw + _i * 8192), 16, 0, 0); } while (0)
; #define PG8_LDA(dst, b, h) do { _Pragma("unroll") for (int m = 0; m < 4; ++m) _Pragma("unroll") for (int k = 0; k < 2; ++k) dst[m][k] = *(const PG8_LAS bf16x8*)(lds + PG8_SA(b, h) + aoff + m * 2048 + k * 1024); } while (0)
; #define PG8_LDB(dst, b, h) do { _Pragma("unroll") for (int n = 0; n < 2; ++n) _Pragma("unroll") for (int k = 0; k < 2; ++k) dst[n][k] = *(const PG8_LAS bf16x8*)(lds + PG8_SB(b, h) + boff + n * 2048 + k * 1024); } while (0)
; #define PG8_MMA(ai, bj, At, Bt) do { __builtin_amdgcn_s_setprio(1); _Pragma("unroll") for (int m = 0; m < 4; ++m) _Pragma("unroll") for (int n = 0; n < 2; ++n) _Pragma("unroll") for (int k = 0; k < 2; ++k) \
;         acc[ai][bj][m][n] = __builtin_amdgcn_mfma_f32_16x16x32_bf16(Bt[n][k], At[m][k], acc[ai][bj][m][n], 0, 0, 0); __builtin_amdgcn_s_setprio(0); } while (0)
; #define PG8_WAIT_V(n) asm volatile("s_waitcnt vmcnt(" #n ")" ::: "memory")
; #define PG8_BAR __builtin_amdgcn_s_barrier()
; template <class Epi, class Sched, bool ALIGN_EPI = false, bool SP2 = false>
; __device__ __forceinline__ void gemm_phase(PG8_LAS unsigned char* lds, const Gemm g, const Sched& S, const Epi& E) {
;     ...
;         for (int t = 0; t < nt; t += 2) {
;             const bool last = (t == nt - 2);
;             const char* a1 = cA + (size_t)(t + 1) * kstep;
;             const char* a2 = last ? nA : cA + (size_t)(t + 2) * kstep; const char* b2 = last ? nB : cB + (size_t)(t + 2) * kstep;
;             const char* a3 = a2 + kstep; const char* b3 = b2 + kstep;
;             if (last && has_next) S.a_ready(nxt);
;             if constexpr (SP2) {
;             PG8_LDB(B0, 0, 0); PG8_LDB(B1, 0, 1); PG8_SCHED; PG8_LDA(At, 0, 0); PG8_STAGE(PG8_SA(1, 1), a1 + hstepA, voffA);
;             PG8_WAIT_V(8); PG8_WAIT_L(0); PG8_BAR; PG8_MMA(0, 0, At, B0); PG8_MMA(0, 1, At, B1); PG8_BAR; PG8_SCHED;
;             PG8_LDA(At, 0, 1); PG8_STAGE(PG8_SB(0, 0), b2, voffB); PG8_STAGE(PG8_SB(0, 1), b2 + hstepB, voffB); PG8_STAGE(PG8_SA(0, 0), a2, voffA);
;             PG8_WAIT_V(8); PG8_WAIT_L(0); PG8_BAR; PG8_MMA(1, 0, At, B0); PG8_MMA(1, 1, At, B1); PG8_BAR; PG8_SCHED;
.LBB0_207:
	s_add_i32 s30, s16, 2
	s_add_u32 s31, s6, 0x80
	s_addc_u32 s17, s7, 0
	s_add_i32 s36, 0, 0x10000
	s_cmp_eq_u32 s88, s16
	s_cselect_b32 s17, s79, s17
	s_cselect_b32 s16, s78, s31
	v_add_u32_e32 v64, s36, v209
	s_cselect_b32 s35, s81, s29
	s_cselect_b32 s34, s80, s28
	s_add_i32 s31, 0, 0x14000
	s_waitcnt lgkmcnt(0)
	ds_read_b128 v[132:135], v64
	ds_read_b128 v[136:139], v64 offset:1024
	ds_read_b128 v[140:143], v64 offset:2048
	ds_read_b128 v[144:147], v64 offset:3072
	v_add_u32_e32 v64, s31, v209
	ds_read_b128 v[148:151], v64
	ds_read_b128 v[152:155], v64 offset:1024
	ds_read_b128 v[182:185], v64 offset:2048
	ds_read_b128 v[186:189], v64 offset:3072
	s_add_i32 m0, s9, 0xc000
	ds_read_b128 v[190:193], v216
	ds_read_b128 v[194:197], v216 offset:1024
	ds_read_b128 v[198:201], v216 offset:2048
	ds_read_b128 v[202:205], v216 offset:3072
	ds_read_b128 v[220:223], v216 offset:4096
	ds_read_b128 v[224:227], v216 offset:5120
	ds_read_b128 v[228:231], v216 offset:6144
	ds_read_b128 v[232:235], v216 offset:7168
	global_load_lds_dwordx4 v180, s[6:7]
	s_add_i32 m0, s9, 0xe000
	s_nop 0
	global_load_lds_dwordx4 v178, s[6:7]
	s_waitcnt vmcnt(8)
	s_waitcnt lgkmcnt(0)
	s_barrier
	s_setprio 1
	s_waitcnt lgkmcnt(0)
	v_mfma_f32_16x16x32_bf16 v[128:131], v[132:135], v[190:193], v[128:131]
	v_mfma_f32_16x16x32_bf16 v[124:127], v[140:143], v[190:193], v[124:127]
	v_mfma_f32_16x16x32_bf16 v[112:115], v[132:135], v[198:201], v[112:115]
	v_mfma_f32_16x16x32_bf16 v[108:111], v[140:143], v[198:201], v[108:111]
	v_mfma_f32_16x16x32_bf16 v[96:99], v[132:135], v[220:223], v[96:99]
	v_mfma_f32_16x16x32_bf16 v[92:95], v[140:143], v[220:223], v[92:95]
	v_mfma_f32_16x16x32_bf16 v[80:83], v[132:135], v[228:231], v[80:83]
	v_mfma_f32_16x16x32_bf16 v[76:79], v[140:143], v[228:231], v[76:79]
	v_mfma_f32_16x16x32_bf16 v[128:131], v[136:139], v[194:197], v[128:131]
	v_mfma_f32_16x16x32_bf16 v[124:127], v[144:147], v[194:197], v[124:127]
	v_mfma_f32_16x16x32_bf16 v[112:115], v[136:139], v[202:205], v[112:115]
	v_mfma_f32_16x16x32_bf16 v[108:111], v[144:147], v[202:205], v[108:111]
	v_mfma_f32_16x16x32_bf16 v[96:99], v[136:139], v[224:227], v[96:99]
	v_mfma_f32_16x16x32_bf16 v[92:95], v[144:147], v[224:227], v[92:95]
	v_mfma_f32_16x16x32_bf16 v[80:83], v[136:139], v[232:235], v[80:83]
	v_mfma_f32_16x16x32_bf16 v[76:79], v[144:147], v[232:235], v[76:79]
	s_setprio 0
	s_setprio 1
	v_mfma_f32_16x16x32_bf16 v[120:123], v[148:151], v[190:193], v[120:123]
	v_mfma_f32_16x16x32_bf16 v[116:119], v[182:185], v[190:193], v[116:119]
	v_mfma_f32_16x16x32_bf16 v[104:107], v[148:151], v[198:201], v[104:107]
	v_mfma_f32_16x16x32_bf16 v[100:103], v[182:185], v[198:201], v[100:103]
	v_mfma_f32_16x16x32_bf16 v[88:91], v[148:151], v[220:223], v[88:91]
	v_mfma_f32_16x16x32_bf16 v[84:87], v[182:185], v[220:223], v[84:87]
	v_mfma_f32_16x16x32_bf16 v[72:75], v[148:151], v[228:231], v[72:75]
	v_mfma_f32_16x16x32_bf16 v[66:69], v[182:185], v[228:231], v[68:71]
	v_mfma_f32_16x16x32_bf16 v[120:123], v[152:155], v[194:197], v[120:123]
	v_mfma_f32_16x16x32_bf16 v[116:119], v[186:189], v[194:197], v[116:119]
	v_mfma_f32_16x16x32_bf16 v[104:107], v[152:155], v[202:205], v[104:107]
	v_mfma_f32_16x16x32_bf16 v[100:103], v[186:189], v[202:205], v[100:103]
	v_mfma_f32_16x16x32_bf16 v[88:91], v[152:155], v[224:227], v[88:91]
	v_mfma_f32_16x16x32_bf16 v[84:87], v[186:189], v[224:227], v[84:87]
	v_mfma_f32_16x16x32_bf16 v[72:75], v[152:155], v[232:235], v[72:75]
	v_mfma_f32_16x16x32_bf16 v[66:69], v[186:189], v[232:235], v[66:69]
	s_setprio 0
	s_barrier
	s_add_i32 s36, s36, s8
	s_mov_b32 m0, s36
	ds_read_b128 v[190:193], v216 offset:16384
	ds_read_b128 v[194:197], v216 offset:17408
	ds_read_b128 v[198:201], v216 offset:18432
	ds_read_b128 v[202:205], v216 offset:19456
	ds_read_b128 v[220:223], v216 offset:20480
	ds_read_b128 v[224:227], v216 offset:21504
	ds_read_b128 v[228:231], v216 offset:22528
	ds_read_b128 v[232:235], v216 offset:23552
	global_load_lds_dwordx4 v160, s[34:35]
	s_add_i32 m0, s36, 0x2000
	s_add_u32 s100, s34, s60
	s_addc_u32 s101, s35, s61
	s_add_i32 s31, s31, s8
	global_load_lds_dwordx4 v164, s[34:35]
	s_add_u32 s34, s34, s94
	s_addc_u32 s35, s35, 0
	s_mov_b32 m0, s31
	s_add_u32 vcc_lo, s16, s60
	s_addc_u32 vcc_hi, s17, s61
	global_load_lds_dwordx4 v160, s[34:35]
	s_add_i32 m0, s31, 0x2000
	s_nop 0
	global_load_lds_dwordx4 v164, s[34:35]
	s_mov_b32 m0, s9
	s_nop 0
	global_load_lds_dwordx4 v158, s[16:17]
	s_mov_b32 m0, s71
	s_nop 0
	global_load_lds_dwordx4 v162, s[16:17]
	s_waitcnt vmcnt(8)
	s_waitcnt lgkmcnt(0)
	s_barrier
; #define PG8_STAGE(bufoff, gbase, voff) do { _Pragma("unroll") for (int _i = 0; _i < 2; ++_i) \
;         __builtin_amdgcn_global_load_lds((const unsigned*)((const char*)(gbase) + (voff)[_i]), (PG8_LAS unsigned*)(lds + (bufoff) + ldsw + _i * 8192), 16, 0, 0); } while (0)
; #define PG8_LDA(dst, b, h) do { _Pragma("unroll") for (int m = 0; m < 4; ++m) _Pragma("unroll") for (int k = 0; k < 2; ++k) dst[m][k] = *(const PG8_LAS bf16x8*)(lds + PG8_SA(b, h) + aoff + m * 2048 + k * 1024); } while (0)
; #define PG8_LDB(dst, b, h) do { _Pragma("unroll") for (int n = 0; n < 2; ++n) _Pragma("unroll") for (int k = 0; k < 2; ++k) dst[n][k] = *(const PG8_LAS bf16x8*)(lds + PG8_SB(b, h) + boff + n * 2048 + k * 1024); } while (0)
; #define PG8_MMA(ai, bj, At, Bt) do { __builtin_amdgcn_s_setprio(1); _Pragma("unroll") for (int m = 0; m < 4; ++m) _Pragma("unroll") for (int n = 0; n < 2; ++n) _Pragma("unroll") for (int k = 0; k < 2; ++k) \
;         acc[ai][bj][m][n] = __builtin_amdgcn_mfma_f32_16x16x32_bf16(Bt[n][k], At[m][k], acc[ai][bj][m][n], 0, 0, 0); __builtin_amdgcn_s_setprio(0); } while (0)
; #define PG8_WAIT_V(n) asm volatile("s_waitcnt vmcnt(" #n ")" ::: "memory")
; #define PG8_WAIT_L(n) asm volatile("s_waitcnt lgkmcnt(" #n ")" ::: "memory")
; #define PG8_BAR __builtin_amdgcn_s_barrier()
; #define PG8_SCHED __builtin_amdgcn_sched_barrier(0)
; template <class Epi, class Sched, bool ALIGN_EPI = false, bool SP2 = false>
; __device__ __forceinline__ void gemm_phase(PG8_LAS unsigned char* lds, const Gemm g, const Sched& S, const Epi& E) {
;     ...
;             PG8_WAIT_V(8); PG8_WAIT_L(0); PG8_BAR; PG8_MMA(1, 0, At, B0); PG8_MMA(1, 1, At, B1); PG8_BAR; PG8_SCHED;
;             PG8_LDB(B0, 1, 0); PG8_LDB(B1, 1, 1); PG8_SCHED; PG8_LDA(At, 1, 0); PG8_STAGE(PG8_SA(0, 1), a2 + hstepA, voffA);
;             PG8_WAIT_V(8); PG8_WAIT_L(0); PG8_BAR; PG8_MMA(0, 0, At, B0); PG8_MMA(0, 1, At, B1); PG8_BAR; PG8_SCHED;
	s_setprio 1
	s_waitcnt lgkmcnt(0)
	v_mfma_f32_16x16x32_bf16 v[60:63], v[132:135], v[190:193], v[60:63]
	v_mfma_f32_16x16x32_bf16 v[56:59], v[140:143], v[190:193], v[56:59]
	v_mfma_f32_16x16x32_bf16 v[44:47], v[132:135], v[198:201], v[44:47]
	v_mfma_f32_16x16x32_bf16 v[40:43], v[140:143], v[198:201], v[40:43]
	v_mfma_f32_16x16x32_bf16 v[28:31], v[132:135], v[220:223], v[28:31]
	v_mfma_f32_16x16x32_bf16 v[24:27], v[140:143], v[220:223], v[24:27]
	v_mfma_f32_16x16x32_bf16 v[12:15], v[132:135], v[228:231], v[12:15]
	v_mfma_f32_16x16x32_bf16 v[8:11], v[140:143], v[228:231], v[8:11]
	v_mfma_f32_16x16x32_bf16 v[60:63], v[136:139], v[194:197], v[60:63]
	v_mfma_f32_16x16x32_bf16 v[56:59], v[144:147], v[194:197], v[56:59]
	v_mfma_f32_16x16x32_bf16 v[44:47], v[136:139], v[202:205], v[44:47]
	v_mfma_f32_16x16x32_bf16 v[40:43], v[144:147], v[202:205], v[40:43]
	v_mfma_f32_16x16x32_bf16 v[28:31], v[136:139], v[224:227], v[28:31]
	v_mfma_f32_16x16x32_bf16 v[24:27], v[144:147], v[224:227], v[24:27]
	v_mfma_f32_16x16x32_bf16 v[12:15], v[136:139], v[232:235], v[12:15]
	v_mfma_f32_16x16x32_bf16 v[8:11], v[144:147], v[232:235], v[8:11]
	s_setprio 0
	s_setprio 1
	v_mfma_f32_16x16x32_bf16 v[52:55], v[148:151], v[190:193], v[52:55]
	v_mfma_f32_16x16x32_bf16 v[48:51], v[182:185], v[190:193], v[48:51]
	v_mfma_f32_16x16x32_bf16 v[36:39], v[148:151], v[198:201], v[36:39]
	v_mfma_f32_16x16x32_bf16 v[32:35], v[182:185], v[198:201], v[32:35]
	v_mfma_f32_16x16x32_bf16 v[20:23], v[148:151], v[220:223], v[20:23]
	v_mfma_f32_16x16x32_bf16 v[16:19], v[182:185], v[220:223], v[16:19]
	v_mfma_f32_16x16x32_bf16 v[4:7], v[148:151], v[228:231], v[4:7]
	v_mfma_f32_16x16x32_bf16 v[0:3], v[182:185], v[228:231], v[0:3]
	v_mfma_f32_16x16x32_bf16 v[52:55], v[152:155], v[194:197], v[52:55]
	v_mfma_f32_16x16x32_bf16 v[48:51], v[186:189], v[194:197], v[48:51]
	v_mfma_f32_16x16x32_bf16 v[36:39], v[152:155], v[202:205], v[36:39]
	v_mfma_f32_16x16x32_bf16 v[32:35], v[186:189], v[202:205], v[32:35]
	v_mfma_f32_16x16x32_bf16 v[20:23], v[152:155], v[224:227], v[20:23]
	v_mfma_f32_16x16x32_bf16 v[16:19], v[186:189], v[224:227], v[16:19]
	v_mfma_f32_16x16x32_bf16 v[4:7], v[152:155], v[232:235], v[4:7]
	v_mfma_f32_16x16x32_bf16 v[0:3], v[186:189], v[232:235], v[0:3]
	s_setprio 0
	s_barrier
	s_add_i32 s31, 0, 0x18000
	v_add_u32_e32 v64, s31, v209
	s_add_i32 s34, 0, 0x1c000
	ds_read_b128 v[132:135], v64
	ds_read_b128 v[136:139], v64 offset:1024
	ds_read_b128 v[140:143], v64 offset:2048
	ds_read_b128 v[144:147], v64 offset:3072
	v_add_u32_e32 v64, s34, v209
	ds_read_b128 v[148:151], v64
	ds_read_b128 v[152:155], v64 offset:1024
	ds_read_b128 v[182:185], v64 offset:2048
	ds_read_b128 v[186:189], v64 offset:3072
	s_add_u32 s16, s16, s94
	s_addc_u32 s17, s17, 0
	s_mov_b32 m0, s12
	ds_read_b128 v[190:193], v216 offset:32768
	ds_read_b128 v[194:197], v216 offset:33792
	ds_read_b128 v[198:201], v216 offset:34816
	ds_read_b128 v[202:205], v216 offset:35840
	ds_read_b128 v[220:223], v216 offset:36864
	ds_read_b128 v[224:227], v216 offset:37888
	ds_read_b128 v[228:231], v216 offset:38912
	ds_read_b128 v[232:235], v216 offset:39936
	global_load_lds_dwordx4 v158, s[16:17]
	s_mov_b32 m0, s13
	s_nop 0
	global_load_lds_dwordx4 v162, s[16:17]
	s_waitcnt vmcnt(8)
	s_waitcnt lgkmcnt(0)
	s_barrier
	s_setprio 1
	s_waitcnt lgkmcnt(0)
	v_mfma_f32_16x16x32_bf16 v[128:131], v[132:135], v[190:193], v[128:131]
	v_mfma_f32_16x16x32_bf16 v[124:127], v[140:143], v[190:193], v[124:127]
	v_mfma_f32_16x16x32_bf16 v[112:115], v[132:135], v[198:201], v[112:115]
	v_mfma_f32_16x16x32_bf16 v[108:111], v[140:143], v[198:201], v[108:111]
	v_mfma_f32_16x16x32_bf16 v[96:99], v[132:135], v[220:223], v[96:99]
	v_mfma_f32_16x16x32_bf16 v[92:95], v[140:143], v[220:223], v[92:95]
	v_mfma_f32_16x16x32_bf16 v[80:83], v[132:135], v[228:231], v[80:83]
	v_mfma_f32_16x16x32_bf16 v[76:79], v[140:143], v[228:231], v[76:79]
	v_mfma_f32_16x16x32_bf16 v[128:131], v[136:139], v[194:197], v[128:131]
	v_mfma_f32_16x16x32_bf16 v[124:127], v[144:147], v[194:197], v[124:127]
	v_mfma_f32_16x16x32_bf16 v[112:115], v[136:139], v[202:205], v[112:115]
	v_mfma_f32_16x16x32_bf16 v[108:111], v[144:147], v[202:205], v[108:111]
	v_mfma_f32_16x16x32_bf16 v[96:99], v[136:139], v[224:227], v[96:99]
	v_mfma_f32_16x16x32_bf16 v[92:95], v[144:147], v[224:227], v[92:95]
	v_mfma_f32_16x16x32_bf16 v[80:83], v[136:139], v[232:235], v[80:83]
	v_mfma_f32_16x16x32_bf16 v[76:79], v[144:147], v[232:235], v[76:79]
	s_setprio 0
	s_setprio 1
	v_mfma_f32_16x16x32_bf16 v[120:123], v[148:151], v[190:193], v[120:123]
	v_mfma_f32_16x16x32_bf16 v[116:119], v[182:185], v[190:193], v[116:119]
	v_mfma_f32_16x16x32_bf16 v[104:107], v[148:151], v[198:201], v[104:107]
	v_mfma_f32_16x16x32_bf16 v[100:103], v[182:185], v[198:201], v[100:103]
	v_mfma_f32_16x16x32_bf16 v[88:91], v[148:151], v[220:223], v[88:91]
	v_mfma_f32_16x16x32_bf16 v[84:87], v[182:185], v[220:223], v[84:87]
	v_mfma_f32_16x16x32_bf16 v[70:73], v[148:151], v[228:231], v[72:75]
	v_mfma_f32_16x16x32_bf16 v[66:69], v[182:185], v[228:231], v[66:69]
	v_mfma_f32_16x16x32_bf16 v[120:123], v[152:155], v[194:197], v[120:123]
	v_mfma_f32_16x16x32_bf16 v[116:119], v[186:189], v[194:197], v[116:119]
	v_mfma_f32_16x16x32_bf16 v[104:107], v[152:155], v[202:205], v[104:107]
	v_mfma_f32_16x16x32_bf16 v[100:103], v[186:189], v[202:205], v[100:103]
	v_mfma_f32_16x16x32_bf16 v[88:91], v[152:155], v[224:227], v[88:91]
	v_mfma_f32_16x16x32_bf16 v[84:87], v[186:189], v[224:227], v[84:87]
	v_mfma_f32_16x16x32_bf16 v[72:75], v[152:155], v[232:235], v[70:73]
	v_mfma_f32_16x16x32_bf16 v[68:71], v[186:189], v[232:235], v[66:69]
	s_setprio 0
	s_barrier
; #define PG8_STAGE(bufoff, gbase, voff) do { _Pragma("unroll") for (int _i = 0; _i < 2; ++_i) \
;         __builtin_amdgcn_global_load_lds((const unsigned*)((const char*)(gbase) + (voff)[_i]), (PG8_LAS unsigned*)(lds + (bufoff) + ldsw + _i * 8192), 16, 0, 0); } while (0)
; #define PG8_LDA(dst, b, h) do { _Pragma("unroll") for (int m = 0; m < 4; ++m) _Pragma("unroll") for (int k = 0; k < 2; ++k) dst[m][k] = *(const PG8_LAS bf16x8*)(lds + PG8_SA(b, h) + aoff + m * 2048 + k * 1024); } while (0)
; #define PG8_MMA(ai, bj, At, Bt) do { __builtin_amdgcn_s_setprio(1); _Pragma("unroll") for (int m = 0; m < 4; ++m) _Pragma("unroll") for (int n = 0; n < 2; ++n) _Pragma("unroll") for (int k = 0; k < 2; ++k) \
;         acc[ai][bj][m][n] = __builtin_amdgcn_mfma_f32_16x16x32_bf16(Bt[n][k], At[m][k], acc[ai][bj][m][n], 0, 0, 0); __builtin_amdgcn_s_setprio(0); } while (0)
; #define PG8_WAIT_V(n) asm volatile("s_waitcnt vmcnt(" #n ")" ::: "memory")
; #define PG8_WAIT_L(n) asm volatile("s_waitcnt lgkmcnt(" #n ")" ::: "memory")
; #define PG8_BAR __builtin_amdgcn_s_barrier()
; #define PG8_SCHED __builtin_amdgcn_sched_barrier(0)
; template <class Epi, class Sched, bool ALIGN_EPI = false, bool SP2 = false>
; __device__ __forceinline__ void gemm_phase(PG8_LAS unsigned char* lds, const Gemm g, const Sched& S, const Epi& E) {
;     ...
;             PG8_LDA(At, 1, 1); PG8_STAGE(PG8_SB(1, 0), b3, voffB); PG8_STAGE(PG8_SB(1, 1), b3 + hstepB, voffB); PG8_STAGE(PG8_SA(1, 0), a3, voffA);
;             PG8_WAIT_V(8); PG8_WAIT_L(0); PG8_BAR; PG8_MMA(1, 0, At, B0); PG8_MMA(1, 1, At, B1); PG8_BAR; PG8_SCHED;
	s_add_i32 s16, s31, s8
	s_mov_b32 m0, s16
	ds_read_b128 v[190:193], v216 offset:49152
	ds_read_b128 v[194:197], v216 offset:50176
	ds_read_b128 v[198:201], v216 offset:51200
	ds_read_b128 v[202:205], v216 offset:52224
	ds_read_b128 v[220:223], v216 offset:53248
	ds_read_b128 v[224:227], v216 offset:54272
	ds_read_b128 v[228:231], v216 offset:55296
	ds_read_b128 v[232:235], v216 offset:56320
	global_load_lds_dwordx4 v160, s[100:101]
	s_add_i32 m0, s16, 0x2000
	s_add_i32 s16, s34, s8
	global_load_lds_dwordx4 v164, s[100:101]
	s_add_u32 s100, s100, s94
	s_addc_u32 s101, s101, 0
	s_mov_b32 m0, s16
	s_nop 0
	global_load_lds_dwordx4 v160, s[100:101]
	s_add_i32 m0, s16, 0x2000
	s_nop 0
	global_load_lds_dwordx4 v164, s[100:101]
	s_mov_b32 m0, s2
	s_nop 0
	global_load_lds_dwordx4 v158, vcc
	s_mov_b32 m0, s33
	s_nop 0
	global_load_lds_dwordx4 v162, vcc
	s_waitcnt vmcnt(8)
	s_waitcnt lgkmcnt(0)
	s_barrier
	s_setprio 1
	s_waitcnt lgkmcnt(0)
	v_mfma_f32_16x16x32_bf16 v[60:63], v[132:135], v[190:193], v[60:63]
	v_mfma_f32_16x16x32_bf16 v[56:59], v[140:143], v[190:193], v[56:59]
	v_mfma_f32_16x16x32_bf16 v[44:47], v[132:135], v[198:201], v[44:47]
	v_mfma_f32_16x16x32_bf16 v[40:43], v[140:143], v[198:201], v[40:43]
	v_mfma_f32_16x16x32_bf16 v[28:31], v[132:135], v[220:223], v[28:31]
	v_mfma_f32_16x16x32_bf16 v[24:27], v[140:143], v[220:223], v[24:27]
	v_mfma_f32_16x16x32_bf16 v[12:15], v[132:135], v[228:231], v[12:15]
	v_mfma_f32_16x16x32_bf16 v[8:11], v[140:143], v[228:231], v[8:11]
	v_mfma_f32_16x16x32_bf16 v[60:63], v[136:139], v[194:197], v[60:63]
	v_mfma_f32_16x16x32_bf16 v[56:59], v[144:147], v[194:197], v[56:59]
	v_mfma_f32_16x16x32_bf16 v[44:47], v[136:139], v[202:205], v[44:47]
	v_mfma_f32_16x16x32_bf16 v[40:43], v[144:147], v[202:205], v[40:43]
	v_mfma_f32_16x16x32_bf16 v[28:31], v[136:139], v[224:227], v[28:31]
	v_mfma_f32_16x16x32_bf16 v[24:27], v[144:147], v[224:227], v[24:27]
	v_mfma_f32_16x16x32_bf16 v[12:15], v[136:139], v[232:235], v[12:15]
	v_mfma_f32_16x16x32_bf16 v[8:11], v[144:147], v[232:235], v[8:11]
	s_setprio 0
	s_setprio 1
	v_mfma_f32_16x16x32_bf16 v[52:55], v[148:151], v[190:193], v[52:55]
	v_mfma_f32_16x16x32_bf16 v[48:51], v[182:185], v[190:193], v[48:51]
	v_mfma_f32_16x16x32_bf16 v[36:39], v[148:151], v[198:201], v[36:39]
	v_mfma_f32_16x16x32_bf16 v[32:35], v[182:185], v[198:201], v[32:35]
	v_mfma_f32_16x16x32_bf16 v[20:23], v[148:151], v[220:223], v[20:23]
	v_mfma_f32_16x16x32_bf16 v[16:19], v[182:185], v[220:223], v[16:19]
	v_mfma_f32_16x16x32_bf16 v[4:7], v[148:151], v[228:231], v[4:7]
	v_mfma_f32_16x16x32_bf16 v[0:3], v[182:185], v[228:231], v[0:3]
	v_mfma_f32_16x16x32_bf16 v[52:55], v[152:155], v[194:197], v[52:55]
	v_mfma_f32_16x16x32_bf16 v[48:51], v[186:189], v[194:197], v[48:51]
	v_mfma_f32_16x16x32_bf16 v[36:39], v[152:155], v[202:205], v[36:39]
	v_mfma_f32_16x16x32_bf16 v[32:35], v[186:189], v[202:205], v[32:35]
	v_mfma_f32_16x16x32_bf16 v[20:23], v[152:155], v[224:227], v[20:23]
	v_mfma_f32_16x16x32_bf16 v[16:19], v[186:189], v[224:227], v[16:19]
	v_mfma_f32_16x16x32_bf16 v[4:7], v[152:155], v[232:235], v[4:7]
	v_mfma_f32_16x16x32_bf16 v[0:3], v[186:189], v[232:235], v[0:3]
	s_setprio 0
	s_barrier
	s_add_u32 s28, s28, 0x100
	s_addc_u32 s29, s29, 0
	s_add_u32 s6, s6, 0x100
	s_addc_u32 s7, s7, 0
	s_cmp_ge_u32 s30, s24
	s_mov_b32 s16, s30
	s_cbranch_scc0 .LBB0_207
	s_branch .LBB0_209

; __global__ void __launch_bounds__(512, 2) mega(Params Pkarg) {
	.amdhsa_kernel _Z4mega6Params
		.amdhsa_group_segment_fixed_size 0
		.amdhsa_private_segment_fixed_size 0
		.amdhsa_kernarg_size 488
		.amdhsa_user_sgpr_count 2
		.amdhsa_user_sgpr_dispatch_ptr 0
		.amdhsa_user_sgpr_queue_ptr 0
		.amdhsa_user_sgpr_kernarg_segment_ptr 1
		.amdhsa_user_sgpr_dispatch_id 0
		.amdhsa_user_sgpr_kernarg_preload_length 0
		.amdhsa_user_sgpr_kernarg_preload_offset 0
		.amdhsa_user_sgpr_private_segment_size 0
		.amdhsa_uses_dynamic_stack 0
		.amdhsa_enable_private_segment 0
		.amdhsa_system_sgpr_workgroup_id_x 1
		.amdhsa_system_sgpr_workgroup_id_y 0
		.amdhsa_system_sgpr_workgroup_id_z 0
		.amdhsa_system_sgpr_workgroup_info 0
		.amdhsa_system_vgpr_workitem_id 2
		.amdhsa_next_free_vgpr 256
		.amdhsa_next_free_sgpr 102
		.amdhsa_accum_offset 256
		.amdhsa_reserve_vcc 1
		.amdhsa_float_round_mode_32 0
		.amdhsa_float_round_mode_16_64 0
		.amdhsa_float_denorm_mode_32 3
		.amdhsa_float_denorm_mode_16_64 3
		.amdhsa_dx10_clamp 1
		.amdhsa_ieee_mode 1
		.amdhsa_fp16_overflow 0
		.amdhsa_tg_split 0
		.amdhsa_exception_fp_ieee_invalid_op 0
		.amdhsa_exception_fp_denorm_src 0
		.amdhsa_exception_fp_ieee_div_zero 0
		.amdhsa_exception_fp_ieee_overflow 0
		.amdhsa_exception_fp_ieee_underflow 0
		.amdhsa_exception_fp_ieee_inexact 0
		.amdhsa_exception_int_div_zero 0
	.end_amdhsa_kernel

; __global__ void __launch_bounds__(512, 2) mega(Params Pkarg) {
amdhsa.kernels:
  - .agpr_count:     0
    .args:
      - .offset:         0
        .size:           232
        .value_kind:     by_value
      - .offset:         232
        .size:           4
        .value_kind:     hidden_block_count_x
      - .offset:         236
        .size:           4
        .value_kind:     hidden_block_count_y
      - .offset:         240
        .size:           4
        .value_kind:     hidden_block_count_z
      - .offset:         244
        .size:           2
        .value_kind:     hidden_group_size_x
      - .offset:         246
        .size:           2
        .value_kind:     hidden_group_size_y
      - .offset:         248
        .size:           2
        .value_kind:     hidden_group_size_z
      - .offset:         250
        .size:           2
        .value_kind:     hidden_remainder_x
      - .offset:         252
        .size:           2
        .value_kind:     hidden_remainder_y
      - .offset:         254
        .size:           2
        .value_kind:     hidden_remainder_z
      - .offset:         272
        .size:           8
        .value_kind:     hidden_global_offset_x
      - .offset:         280
        .size:           8
        .value_kind:     hidden_global_offset_y
      - .offset:         288
        .size:           8
        .value_kind:     hidden_global_offset_z
      - .offset:         296
        .size:           2
        .value_kind:     hidden_grid_dims
      - .offset:         320
        .size:           8
        .value_kind:     hidden_multigrid_sync_arg
      - .offset:         352
        .size:           4
        .value_kind:     hidden_dynamic_lds_size
    .group_segment_fixed_size: 0
    .kernarg_segment_align: 8
    .kernarg_segment_size: 488
    .language:       OpenCL C
    .language_version:
      - 2
      - 0
    .max_flat_workgroup_size: 512
    .name:           _Z4mega6Params
    .private_segment_fixed_size: 0
    .sgpr_count:     108
    .sgpr_spill_count: 425
    .symbol:         _Z4mega6Params.kd
    .uniform_work_group_size: 1
    .uses_dynamic_stack: false
    .vgpr_count:     256
    .vgpr_spill_count: 0
    .wavefront_size: 64
